# MLA attention loop: running-max chain moved to the head of the PV MFMA block, in-place score rescales moved into that block (odd scores of the first half rescaled in place)
# baseline (speedup 1.0000x reference)
; __device__ __forceinline__ void finishSM(f32x16& p0, f32x16& p1, float alpha, float& l_reg, bf16x8& pa0, bf16x8& pa1, bf16x8& pa2, bf16x8& pa3) {
; #pragma unroll
;     for (int r = 0; r < 16; ++r) p1[r] = __builtin_amdgcn_exp2f(p1[r]);
;     float ps = 0;
; #pragma unroll
;     for (int r = 0; r < 16; ++r) ps += p0[r];
; #pragma unroll
;     for (int r = 0; r < 16; ++r) ps += p1[r];
;     { auto rr = __builtin_amdgcn_permlane32_swap(__float_as_uint(ps), __float_as_uint(ps), false, false);
;       ps = __uint_as_float(rr[0]) + __uint_as_float(rr[1]); }
;     l_reg = l_reg * alpha + ps;
;     ...
;     PK4(p0, 0, pa0); PK4(p0, 8, pa1); PK4(p1, 0, pa2); PK4(p1, 8, pa3);
.LBB0_219:
	ds_read_b128 v[64:67], v184 offset:57344
	ds_read_b128 v[68:71], v216 offset:12288
	ds_read_b128 v[222:225], v192 offset:57344
	ds_read_b128 v[226:229], v208 offset:12288
	v_exp_f32_e32 v207, v130
	v_add_f32_e32 v130, 0, v219
	s_waitcnt lgkmcnt(3)
	v_mfma_f32_32x32x16_bf16 v[80:95], v[64:67], v[126:129], 0
	v_add_f32_e32 v130, v221, v130
	v_add_f32_e32 v130, v157, v130
	v_add_f32_e32 v130, v220, v130
	v_add_f32_e32 v130, v156, v130
	v_add_f32_e32 v130, v218, v130
	v_add_f32_e32 v130, v154, v130
	v_add_f32_e32 v130, v155, v130
	s_waitcnt lgkmcnt(2)
	v_mfma_f32_32x32x16_bf16 v[64:79], v[68:71], v[126:129], 0
	v_add_f32_e32 v130, v151, v130
	v_add_f32_e32 v130, v153, v130
	v_add_f32_e32 v130, v150, v130
	v_add_f32_e32 v130, v152, v130
	v_exp_f32_e32 v142, v142
	v_add_f32_e32 v130, v147, v130
	v_exp_f32_e32 v143, v143
	s_waitcnt lgkmcnt(1)
	v_mfma_f32_32x32x16_bf16 v[80:95], v[222:225], v[122:125], v[80:95]
	v_add_f32_e32 v130, v149, v130
	v_exp_f32_e32 v140, v140
	v_add_f32_e32 v130, v146, v130
	v_exp_f32_e32 v141, v141
	v_add_f32_e32 v130, v148, v130
	v_exp_f32_e32 v134, v134
	v_add_f32_e32 v130, v142, v130
	s_waitcnt lgkmcnt(0)
	v_mfma_f32_32x32x16_bf16 v[64:79], v[226:229], v[122:125], v[64:79]
	ds_read_b128 v[222:225], v190 offset:57344
	ds_read_b128 v[226:229], v206 offset:12288
	v_exp_f32_e32 v135, v135
	v_add_f32_e32 v130, v143, v130
	v_exp_f32_e32 v191, v132
	v_add_f32_e32 v130, v140, v130
	v_exp_f32_e32 v205, v133
	v_add_f32_e32 v130, v141, v130
	s_waitcnt lgkmcnt(1)
	v_mfma_f32_32x32x16_bf16 v[80:95], v[222:225], v[118:121], v[80:95]
	v_add_f32_e32 v130, v134, v130
	v_exp_f32_e32 v210, v131
	v_add_f32_e32 v130, v135, v130
	v_exp_f32_e32 v144, v144
	v_add_f32_e32 v130, v191, v130
	v_exp_f32_e32 v145, v145
	v_add_f32_e32 v130, v205, v130
	s_waitcnt lgkmcnt(0)
	v_mfma_f32_32x32x16_bf16 v[64:79], v[226:229], v[118:121], v[64:79]
	ds_read_b128 v[222:225], v173 offset:57344
	ds_read_b128 v[226:229], v202 offset:12288
	v_exp_f32_e32 v138, v138
	v_add_f32_e32 v130, v207, v130
	v_exp_f32_e32 v139, v139
	v_add_f32_e32 v130, v210, v130
	v_exp_f32_e32 v136, v136
	v_add_f32_e32 v130, v144, v130
	s_waitcnt lgkmcnt(1)
	v_mfma_f32_32x32x16_bf16 v[80:95], v[222:225], v[114:117], v[80:95]
	v_exp_f32_e32 v137, v137
	v_add_f32_e32 v130, v145, v130
	v_add_f32_e32 v130, v138, v130
	v_add_f32_e32 v130, v139, v130
	v_add_f32_e32 v130, v136, v130
	s_waitcnt lgkmcnt(0)
	v_mfma_f32_32x32x16_bf16 v[64:79], v[226:229], v[114:117], v[64:79]
	ds_read_b128 v[222:225], v184 offset:57472
	ds_read_b128 v[226:229], v216 offset:12416
	s_waitcnt lgkmcnt(1)
	v_mfma_f32_32x32x16_bf16 v[80:95], v[222:225], v[110:113], v[80:95]
	s_waitcnt lgkmcnt(0)
	v_mfma_f32_32x32x16_bf16 v[64:79], v[226:229], v[110:113], v[64:79]
	ds_read_b128 v[222:225], v192 offset:57472
	ds_read_b128 v[226:229], v208 offset:12416
	s_waitcnt lgkmcnt(1)
	v_mfma_f32_32x32x16_bf16 v[80:95], v[222:225], v[106:109], v[80:95]
	s_waitcnt lgkmcnt(0)
	v_mfma_f32_32x32x16_bf16 v[64:79], v[226:229], v[106:109], v[64:79]
	ds_read_b128 v[222:225], v190 offset:57472
	ds_read_b128 v[226:229], v206 offset:12416
	s_waitcnt lgkmcnt(1)
	v_mfma_f32_32x32x16_bf16 v[80:95], v[222:225], v[102:105], v[80:95]
	s_waitcnt lgkmcnt(0)
	v_mfma_f32_32x32x16_bf16 v[64:79], v[226:229], v[102:105], v[64:79]
	ds_read_b128 v[222:225], v173 offset:57472
	ds_read_b128 v[226:229], v202 offset:12416
	s_waitcnt lgkmcnt(1)
	v_mfma_f32_32x32x16_bf16 v[80:95], v[222:225], v[98:101], v[80:95]
	s_waitcnt lgkmcnt(0)
	v_mfma_f32_32x32x16_bf16 v[64:79], v[226:229], v[98:101], v[64:79]
	ds_read_b128 v[222:225], v184 offset:57600
	ds_read_b128 v[226:229], v216 offset:12544
	ds_read_b128 v[230:233], v181
	s_waitcnt lgkmcnt(0)
	v_mfma_f32_32x32x16_bf16 v[80:95], v[222:225], v[230:233], v[80:95]
	v_mfma_f32_32x32x16_bf16 v[64:79], v[226:229], v[230:233], v[64:79]
	ds_read_b128 v[222:225], v192 offset:57600
	ds_read_b128 v[226:229], v208 offset:12544
	ds_read_b128 v[230:233], v181 offset:8192
	s_waitcnt lgkmcnt(0)
	v_mfma_f32_32x32x16_bf16 v[80:95], v[222:225], v[230:233], v[80:95]
	v_mfma_f32_32x32x16_bf16 v[64:79], v[226:229], v[230:233], v[64:79]
	ds_read_b128 v[222:225], v190 offset:57600
	ds_read_b128 v[226:229], v206 offset:12544
	ds_read_b128 v[230:233], v181 offset:16384
	s_waitcnt lgkmcnt(0)
	v_mfma_f32_32x32x16_bf16 v[80:95], v[222:225], v[230:233], v[80:95]
	v_mfma_f32_32x32x16_bf16 v[64:79], v[226:229], v[230:233], v[64:79]
	ds_read_b128 v[222:225], v173 offset:57600
	ds_read_b128 v[226:229], v202 offset:12544
	ds_read_b128 v[230:233], v181 offset:24576
	s_waitcnt lgkmcnt(0)
; template <int D0> __device__ __forceinline__ void pv_one(f32x16& od, int vb, bf16x8 pa0, bf16x8 pa1, bf16x8 pa2, bf16x8 pa3) {
;     const s16x4 l0 = tr_read<v_rd_off(D0, 0, 0)>(vb), h0 = tr_read<v_rd_off(D0, 0, 1)>(vb), l1 = tr_read<v_rd_off(D0, 1, 0)>(vb), h1 = tr_read<v_rd_off(D0, 1, 1)>(vb);
;     const s16x4 l2 = tr_read<v_rd_off(D0, 2, 0)>(vb), h2 = tr_read<v_rd_off(D0, 2, 1)>(vb), l3 = tr_read<v_rd_off(D0, 3, 0)>(vb), h3 = tr_read<v_rd_off(D0, 3, 1)>(vb);
;     asm volatile("s_waitcnt lgkmcnt(0)" ::: "memory"); SBAR();
;     ...
;     od = __builtin_amdgcn_mfma_f32_32x32x16_bf16(pa0, PK(l0, h0), od, 0, 0, 0);
;     od = __builtin_amdgcn_mfma_f32_32x32x16_bf16(pa1, PK(l1, h1), od, 0, 0, 0);
;     od = __builtin_amdgcn_mfma_f32_32x32x16_bf16(pa2, PK(l2, h2), od, 0, 0, 0);
;     od = __builtin_amdgcn_mfma_f32_32x32x16_bf16(pa3, PK(l3, h3), od, 0, 0, 0);
;     ...
; }
; __device__ __forceinline__ void pv_d0(f32x16* o, int vb, bf16x8 pa0, bf16x8 pa1, bf16x8 pa2, bf16x8 pa3) {
;     pv_one<0>(o[0], vb, pa0, pa1, pa2, pa3); pv_one<1>(o[1], vb, pa0, pa1, pa2, pa3); pv_one<2>(o[2], vb, pa0, pa1, pa2, pa3); pv_one<3>(o[3], vb, pa0, pa1, pa2, pa3);
; }
; __device__ __forceinline__ void partialSM(f32x16& p0, f32x16& p1, float& m_reg, float& mn, float& alpha, const float C, const float thr) {
;     float pmax = p0[0];
; #pragma unroll
;     for (int r = 1; r < 16; ++r) pmax = fmaxf(pmax, p0[r]);
; #pragma unroll
;     for (int r = 0; r < 16; ++r) pmax = fmaxf(pmax, p1[r]);
;     { auto rr = __builtin_amdgcn_permlane32_swap(__float_as_uint(pmax), __float_as_uint(pmax), false, false);
;       pmax = fmaxf(__uint_as_float(rr[0]), __uint_as_float(rr[1])); }
;     if (__builtin_expect(__all(pmax - m_reg <= thr), 1)) { mn = m_reg; alpha = 1.f; }
;     else { mn = fmaxf(m_reg, pmax); alpha = __builtin_amdgcn_exp2f((m_reg - mn) * C); m_reg = mn; }
;     const float mnC = -mn * C;
; #pragma unroll
;     for (int r = 0; r < 16; ++r) p0[r] = fmaf(p0[r], C, mnC);
; #pragma unroll
;     for (int r = 0; r < 16; ++r) p1[r] = fmaf(p1[r], C, mnC);
; #pragma unroll
;     for (int r = 0; r < 16; ++r) p0[r] = __builtin_amdgcn_exp2f(p0[r]);
; }
; __device__ __forceinline__ void finishSM(f32x16& p0, f32x16& p1, float alpha, float& l_reg, bf16x8& pa0, bf16x8& pa1, bf16x8& pa2, bf16x8& pa3) {
; #pragma unroll
;     for (int r = 0; r < 16; ++r) p1[r] = __builtin_amdgcn_exp2f(p1[r]);
;     float ps = 0;
	v_mfma_f32_32x32x16_bf16 v[80:95], v[222:225], v[230:233], v[80:95]
	v_add_f32_e32 v222, v137, v130
	v_mov_b32_e32 v223, v222
	v_cvt_pk_bf16_f32 v130, v219, v221
	v_cvt_pk_bf16_f32 v131, v157, v220
	v_cvt_pk_bf16_f32 v132, v156, v218
	v_cvt_pk_bf16_f32 v133, v154, v155
	v_cvt_pk_bf16_f32 v154, v151, v153
	v_mfma_f32_32x32x16_bf16 v[64:79], v[226:229], v[230:233], v[64:79]
	v_cvt_pk_bf16_f32 v155, v150, v152
	v_cvt_pk_bf16_f32 v156, v147, v149
	v_cvt_pk_bf16_f32 v157, v146, v148
	v_cvt_pk_bf16_f32 v218, v142, v143
	v_cvt_pk_bf16_f32 v219, v140, v141
	v_cvt_pk_bf16_f32 v220, v134, v135
	v_cvt_pk_bf16_f32 v221, v191, v205
	v_cvt_pk_bf16_f32 v224, v207, v210
	v_cvt_pk_bf16_f32 v225, v144, v145
	v_cvt_pk_bf16_f32 v226, v138, v139
	v_cvt_pk_bf16_f32 v227, v136, v137
	s_nop 0
	v_permlane32_swap_b32_e32 v222, v223
	v_permlane32_swap_b32_e32 v130, v132
	v_permlane32_swap_b32_e32 v225, v227
	v_permlane32_swap_b32_e32 v131, v133
	v_permlane32_swap_b32_e32 v154, v156
	v_permlane32_swap_b32_e32 v155, v157
	v_permlane32_swap_b32_e32 v218, v220
	v_permlane32_swap_b32_e32 v219, v221
	v_permlane32_swap_b32_e32 v224, v226
	s_cmp_lt_u32 s69, s68
	s_cselect_b32 s14, 0, s68
	s_cselect_b32 s15, s25, s28
	s_lshl_b32 s14, s14, 6
	s_sub_i32 s14, s15, s14
	s_add_i32 s14, s37, s14
	s_ashr_i32 s15, s14, 31
	v_lshl_add_u64 v[134:135], s[14:15], 0, v[174:175]
	v_lshl_add_u64 v[136:137], v[176:177], 0, s[14:15]
	v_lshlrev_b64 v[134:135], 12, v[134:135]
	v_lshlrev_b64 v[136:137], 12, v[136:137]
	v_lshl_add_u64 v[134:135], v[178:179], 0, v[134:135]
	v_lshl_add_u64 v[138:139], v[178:179], 0, v[136:137]
	v_mad_i64_i32 v[142:143], s[20:21], v164, s14, 0
	v_mad_i64_i32 v[146:147], s[20:21], v168, s14, 0
	v_mad_i64_i32 v[150:151], s[14:15], v172, s14, 0
	global_load_dwordx4 v[134:137], v[134:135], off offset:256
	s_nop 0
	global_load_dwordx4 v[138:141], v[138:139], off offset:256
	v_lshl_add_u64 v[142:143], v[142:143], 1, v[162:163]
	v_lshl_add_u64 v[146:147], v[146:147], 1, v[166:167]
	v_lshl_add_u64 v[150:151], v[150:151], 1, v[170:171]
	global_load_dwordx4 v[142:145], v[142:143], off
	s_nop 0
	global_load_dwordx4 v[146:149], v[146:147], off
	s_nop 0
	global_load_dwordx4 v[150:153], v[150:151], off
	ds_read_b64_tr_b16 v[228:229], v200 offset:0
	ds_read_b64_tr_b16 v[230:231], v200 offset:0x800
	ds_read_b64_tr_b16 v[232:233], v200 offset:0x1000
	ds_read_b64_tr_b16 v[234:235], v200 offset:0x1800
	ds_read_b64_tr_b16 v[236:237], v200 offset:0x2000
	ds_read_b64_tr_b16 v[238:239], v200 offset:0x2800
	ds_read_b64_tr_b16 v[240:241], v200 offset:0x3000
	ds_read_b64_tr_b16 v[242:243], v200 offset:0x3800
	s_waitcnt lgkmcnt(0)
	s_nop 0
	v_mfma_f32_32x32x16_bf16 v[48:63], v[130:133], v[228:231], v[48:63]
	ds_read_b64_tr_b16 v[228:229], v200 offset:0x200
	ds_read_b64_tr_b16 v[230:231], v200 offset:0xa00
	v_max_f32_e32 v248, v81, v81
	v_max_f32_e32 v249, v80, v80
	v_max_f32_e32 v248, v249, v248
	v_max3_f32 v248, v248, v82, v83
	v_max3_f32 v248, v248, v84, v85
	v_max3_f32 v248, v248, v86, v87
	v_mfma_f32_32x32x16_bf16 v[48:63], v[154:157], v[232:235], v[48:63]
	ds_read_b64_tr_b16 v[232:233], v200 offset:0x1200
	ds_read_b64_tr_b16 v[234:235], v200 offset:0x1a00
	v_max3_f32 v248, v248, v88, v89
	v_max3_f32 v248, v248, v90, v91
	v_max3_f32 v248, v248, v92, v93
	v_max3_f32 v248, v248, v94, v95
	v_max3_f32 v248, v248, v64, v65
	v_max3_f32 v248, v248, v66, v67
	v_mfma_f32_32x32x16_bf16 v[48:63], v[218:221], v[236:239], v[48:63]
	ds_read_b64_tr_b16 v[236:237], v200 offset:0x2200
	ds_read_b64_tr_b16 v[238:239], v200 offset:0x2a00
	v_max3_f32 v248, v248, v68, v69
	v_max3_f32 v248, v248, v70, v71
	v_max3_f32 v248, v248, v72, v73
	v_max3_f32 v248, v248, v74, v75
	v_max3_f32 v248, v248, v76, v77
	v_max3_f32 v248, v248, v78, v79
	v_mfma_f32_32x32x16_bf16 v[48:63], v[224:227], v[240:243], v[48:63]
	ds_read_b64_tr_b16 v[240:241], v200 offset:0x3200
	ds_read_b64_tr_b16 v[242:243], v200 offset:0x3a00
	v_mov_b32_e32 v249, v248
	s_nop 1
	v_permlane32_swap_b32_e32 v248, v249
	v_max_f32_e32 v249, v249, v249
	v_max_f32_e32 v248, v248, v248
	v_max_f32_e32 v248, v248, v249
	s_waitcnt lgkmcnt(0)
	v_mfma_f32_32x32x16_bf16 v[32:47], v[130:133], v[228:231], v[32:47]
	ds_read_b64_tr_b16 v[228:229], v200 offset:0x400
	ds_read_b64_tr_b16 v[230:231], v200 offset:0xc00
	v_sub_f32_e32 v249, v248, v204
	v_cmp_ge_f32_e32 vcc, s72, v249
	v_max_f32_e32 v249, v204, v204
	v_max_f32_e32 v248, v249, v248
	v_sub_f32_e32 v249, v204, v248
	v_mul_f32_e32 v249, 0x3dd53b94, v249
	v_mfma_f32_32x32x16_bf16 v[32:47], v[154:157], v[232:235], v[32:47]
	ds_read_b64_tr_b16 v[232:233], v200 offset:0x1400
	ds_read_b64_tr_b16 v[234:235], v200 offset:0x1c00
	v_exp_f32_e32 v249, v249
	s_cmp_eq_u64 vcc, exec
	s_cselect_b64 s[14:15], -1, 0
	v_cndmask_b32_e64 v250, v249, 1.0, s[14:15]
	v_cmp_gt_f32_e32 vcc, 1.0, v250
	v_mfma_f32_32x32x16_bf16 v[32:47], v[218:221], v[236:239], v[32:47]
	ds_read_b64_tr_b16 v[236:237], v200 offset:0x2400
	ds_read_b64_tr_b16 v[238:239], v200 offset:0x2c00
	v_cndmask_b32_e64 v251, v248, v204, s[14:15]
	v_mul_f32_e32 v249, 0xbdd53b94, v251
	v_fmamk_f32 v80, v80, 0x3dd53b94, v249
	v_fmamk_f32 v87, v87, 0x3dd53b94, v249
	v_mfma_f32_32x32x16_bf16 v[32:47], v[224:227], v[240:243], v[32:47]
	ds_read_b64_tr_b16 v[240:241], v200 offset:0x3400
	ds_read_b64_tr_b16 v[242:243], v200 offset:0x3c00
	v_fmamk_f32 v82, v82, 0x3dd53b94, v249
	v_fmamk_f32 v84, v84, 0x3dd53b94, v249
	v_fmamk_f32 v86, v86, 0x3dd53b94, v249
	v_fmamk_f32 v88, v88, 0x3dd53b94, v249
	s_waitcnt lgkmcnt(0)
	v_mfma_f32_32x32x16_bf16 v[16:31], v[130:133], v[228:231], v[16:31]
	ds_read_b64_tr_b16 v[228:229], v200 offset:0x600
	ds_read_b64_tr_b16 v[230:231], v200 offset:0xe00
	v_fmamk_f32 v90, v90, 0x3dd53b94, v249
	v_fmamk_f32 v92, v92, 0x3dd53b94, v249
	v_fmamk_f32 v94, v94, 0x3dd53b94, v249
	v_fmamk_f32 v81, v81, 0x3dd53b94, v249
	v_mfma_f32_32x32x16_bf16 v[16:31], v[154:157], v[232:235], v[16:31]
	ds_read_b64_tr_b16 v[232:233], v200 offset:0x1600
	ds_read_b64_tr_b16 v[234:235], v200 offset:0x1e00
	v_fmamk_f32 v83, v83, 0x3dd53b94, v249
	v_fmamk_f32 v85, v85, 0x3dd53b94, v249
	v_fmamk_f32 v89, v89, 0x3dd53b94, v249
	v_fmamk_f32 v91, v91, 0x3dd53b94, v249
	v_mfma_f32_32x32x16_bf16 v[16:31], v[218:221], v[236:239], v[16:31]
	ds_read_b64_tr_b16 v[236:237], v200 offset:0x2600
	ds_read_b64_tr_b16 v[238:239], v200 offset:0x2e00
	v_fmamk_f32 v93, v93, 0x3dd53b94, v249
	v_fmamk_f32 v95, v95, 0x3dd53b94, v249
	v_mfma_f32_32x32x16_bf16 v[16:31], v[224:227], v[240:243], v[16:31]
	ds_read_b64_tr_b16 v[240:241], v200 offset:0x3600
	ds_read_b64_tr_b16 v[242:243], v200 offset:0x3e00
	s_waitcnt lgkmcnt(0)
	v_mfma_f32_32x32x16_bf16 v[0:15], v[130:133], v[228:231], v[0:15]
	v_mfma_f32_32x32x16_bf16 v[0:15], v[154:157], v[232:235], v[0:15]
	v_mfma_f32_32x32x16_bf16 v[0:15], v[218:221], v[236:239], v[0:15]
	v_mfma_f32_32x32x16_bf16 v[0:15], v[224:227], v[240:243], v[0:15]
	v_mov_b32_e32 v225, v250
	s_barrier
; __device__ __forceinline__ void partialSM(f32x16& p0, f32x16& p1, float& m_reg, float& mn, float& alpha, const float C, const float thr) {
;     float pmax = p0[0];
; #pragma unroll
;     for (int r = 1; r < 16; ++r) pmax = fmaxf(pmax, p0[r]);
; #pragma unroll
;     for (int r = 0; r < 16; ++r) pmax = fmaxf(pmax, p1[r]);
;     { auto rr = __builtin_amdgcn_permlane32_swap(__float_as_uint(pmax), __float_as_uint(pmax), false, false);
;       pmax = fmaxf(__uint_as_float(rr[0]), __uint_as_float(rr[1])); }
;     if (__builtin_expect(__all(pmax - m_reg <= thr), 1)) { mn = m_reg; alpha = 1.f; }
;     else { mn = fmaxf(m_reg, pmax); alpha = __builtin_amdgcn_exp2f((m_reg - mn) * C); m_reg = mn; }
;     const float mnC = -mn * C;
; #pragma unroll
;     for (int r = 0; r < 16; ++r) p0[r] = fmaf(p0[r], C, mnC);
; #pragma unroll
;     for (int r = 0; r < 16; ++r) p1[r] = fmaf(p1[r], C, mnC);
; #pragma unroll
;     for (int r = 0; r < 16; ++r) p0[r] = __builtin_amdgcn_exp2f(p0[r]);
; }
	s_waitcnt vmcnt(4)
	ds_write_b128 v186, v[134:137]
	s_waitcnt vmcnt(3)
	ds_write_b128 v188, v[138:141]
	s_waitcnt vmcnt(2)
	ds_write_b128 v194, v[142:145] offset:32768
	s_waitcnt vmcnt(1)
	ds_write_b128 v196, v[146:149] offset:32768
	s_waitcnt vmcnt(0)
	ds_write_b128 v198, v[150:153] offset:32768
	s_cbranch_vccz .LBB0_223
	s_and_saveexec_b64 s[20:21], s[12:13]
	ds_write_b32 v165, v225 offset:128
	s_or_b64 exec, exec, s[20:21]
	s_waitcnt lgkmcnt(0)
	v_add_u32_e32 v131, v161, v96
	ds_read_b128 v[132:135], v131 offset:224
	ds_read_b128 v[136:139], v131 offset:192
	ds_read_b128 v[140:143], v131 offset:160
	ds_read_b128 v[144:147], v131 offset:128
	s_waitcnt lgkmcnt(3)
	v_pk_mul_f32 v[60:61], v[60:61], v[132:133]
	s_waitcnt lgkmcnt(2)
	v_pk_mul_f32 v[56:57], v[56:57], v[136:137]
	s_waitcnt lgkmcnt(1)
	v_pk_mul_f32 v[52:53], v[52:53], v[140:141]
	v_pk_mul_f32 v[62:63], v[62:63], v[134:135]
	v_pk_mul_f32 v[58:59], v[58:59], v[138:139]
	v_pk_mul_f32 v[54:55], v[54:55], v[142:143]
	s_waitcnt lgkmcnt(0)
	v_pk_mul_f32 v[50:51], v[50:51], v[146:147]
	v_pk_mul_f32 v[48:49], v[48:49], v[144:145]
	v_pk_mul_f32 v[44:45], v[44:45], v[132:133]
	v_pk_mul_f32 v[40:41], v[40:41], v[136:137]
	v_pk_mul_f32 v[36:37], v[36:37], v[140:141]
	v_pk_mul_f32 v[46:47], v[46:47], v[134:135]
	v_pk_mul_f32 v[42:43], v[42:43], v[138:139]
	v_pk_mul_f32 v[38:39], v[38:39], v[142:143]
	v_pk_mul_f32 v[34:35], v[34:35], v[146:147]
	v_pk_mul_f32 v[32:33], v[32:33], v[144:145]
	v_pk_mul_f32 v[28:29], v[28:29], v[132:133]
	v_pk_mul_f32 v[24:25], v[24:25], v[136:137]
	v_pk_mul_f32 v[20:21], v[20:21], v[140:141]
	v_pk_mul_f32 v[30:31], v[30:31], v[134:135]
	v_pk_mul_f32 v[26:27], v[26:27], v[138:139]
	v_pk_mul_f32 v[22:23], v[22:23], v[142:143]
	v_pk_mul_f32 v[18:19], v[18:19], v[146:147]
	v_pk_mul_f32 v[16:17], v[16:17], v[144:145]
	v_pk_mul_f32 v[12:13], v[12:13], v[132:133]
	v_pk_mul_f32 v[8:9], v[8:9], v[136:137]
	v_pk_mul_f32 v[4:5], v[4:5], v[140:141]
	v_pk_mul_f32 v[14:15], v[14:15], v[134:135]
	v_pk_mul_f32 v[10:11], v[10:11], v[138:139]
	v_pk_mul_f32 v[6:7], v[6:7], v[142:143]
	v_pk_mul_f32 v[2:3], v[2:3], v[146:147]
	v_pk_mul_f32 v[0:1], v[0:1], v[144:145]
.LBB0_223:
	v_cndmask_b32_e64 v204, v248, v204, s[14:15]
	v_mul_f32_e32 v138, 0xbdd53b94, v204
	v_fmamk_f32 v140, v70, 0x3dd53b94, v138
	v_exp_f32_e32 v130, v80
	v_exp_f32_e32 v224, v87
	v_fmamk_f32 v145, v64, 0x3dd53b94, v138
	v_fmamk_f32 v144, v66, 0x3dd53b94, v138
	v_fmamk_f32 v143, v68, 0x3dd53b94, v138
	v_fmamk_f32 v139, v72, 0x3dd53b94, v138
	v_fmamk_f32 v146, v74, 0x3dd53b94, v138
	v_fmamk_f32 v142, v76, 0x3dd53b94, v138
	v_fmamk_f32 v141, v78, 0x3dd53b94, v138
	v_exp_f32_e32 v131, v82
	v_exp_f32_e32 v132, v84
	v_exp_f32_e32 v133, v86
	v_exp_f32_e32 v137, v88
	v_exp_f32_e32 v136, v90
	v_exp_f32_e32 v135, v92
	v_exp_f32_e32 v134, v94
	v_fmamk_f32 v147, v65, 0x3dd53b94, v138
	v_fmamk_f32 v156, v67, 0x3dd53b94, v138
	v_fmamk_f32 v157, v69, 0x3dd53b94, v138
	v_fmamk_f32 v191, v71, 0x3dd53b94, v138
	v_fmamk_f32 v205, v73, 0x3dd53b94, v138
	v_fmamk_f32 v207, v75, 0x3dd53b94, v138
	v_fmamk_f32 v210, v77, 0x3dd53b94, v138
	v_fmac_f32_e32 v138, 0x3dd53b94, v79
	v_exp_f32_e32 v211, v81
	v_exp_f32_e32 v212, v83
	v_exp_f32_e32 v213, v85
	v_exp_f32_e32 v228, v89
	v_exp_f32_e32 v229, v91
	v_exp_f32_e32 v230, v93
	v_exp_f32_e32 v231, v95
	s_waitcnt lgkmcnt(0)
	s_barrier
	ds_read_b128 v[64:67], v184 offset:32768
	ds_read_b128 v[68:71], v184 offset:45056
	ds_read_b128 v[148:151], v192 offset:32768
	ds_read_b128 v[152:155], v192 offset:45056
	v_exp_f32_e32 v145, v145
	v_exp_f32_e32 v147, v147
	s_waitcnt lgkmcnt(3)
	v_mfma_f32_32x32x16_bf16 v[80:95], v[64:67], v[126:129], 0
	v_exp_f32_e32 v144, v144
	v_exp_f32_e32 v143, v143
	v_exp_f32_e32 v140, v140
	v_exp_f32_e32 v139, v139
	v_exp_f32_e32 v146, v146
	v_exp_f32_e32 v142, v142
	v_exp_f32_e32 v141, v141
	s_waitcnt lgkmcnt(2)
	v_mfma_f32_32x32x16_bf16 v[64:79], v[68:71], v[126:129], 0
	v_exp_f32_e32 v138, v138
	s_waitcnt lgkmcnt(0)
	v_mfma_f32_32x32x16_bf16 v[64:79], v[152:155], v[122:125], v[64:79]
	v_mfma_f32_32x32x16_bf16 v[80:95], v[148:151], v[122:125], v[80:95]
	ds_read_b128 v[148:151], v190 offset:32768
	ds_read_b128 v[152:155], v190 offset:45056
	s_waitcnt lgkmcnt(0)
	v_mfma_f32_32x32x16_bf16 v[64:79], v[152:155], v[118:121], v[64:79]
	v_mfma_f32_32x32x16_bf16 v[80:95], v[148:151], v[118:121], v[80:95]
	ds_read_b128 v[148:151], v173 offset:32768
	ds_read_b128 v[152:155], v173 offset:45056
	s_waitcnt lgkmcnt(0)
	v_mfma_f32_32x32x16_bf16 v[64:79], v[152:155], v[114:117], v[64:79]
	v_mfma_f32_32x32x16_bf16 v[80:95], v[148:151], v[114:117], v[80:95]
	ds_read_b128 v[148:151], v184 offset:32896
	ds_read_b128 v[152:155], v184 offset:45184
	s_waitcnt lgkmcnt(0)
	v_mfma_f32_32x32x16_bf16 v[64:79], v[152:155], v[110:113], v[64:79]
	v_mfma_f32_32x32x16_bf16 v[80:95], v[148:151], v[110:113], v[80:95]
	ds_read_b128 v[148:151], v192 offset:32896
	ds_read_b128 v[152:155], v192 offset:45184
	s_waitcnt lgkmcnt(0)
	v_mfma_f32_32x32x16_bf16 v[64:79], v[152:155], v[106:109], v[64:79]
	v_mfma_f32_32x32x16_bf16 v[80:95], v[148:151], v[106:109], v[80:95]
	ds_read_b128 v[148:151], v190 offset:32896
	ds_read_b128 v[152:155], v190 offset:45184
	s_waitcnt lgkmcnt(0)
	v_mfma_f32_32x32x16_bf16 v[64:79], v[152:155], v[102:105], v[64:79]
	v_mfma_f32_32x32x16_bf16 v[80:95], v[148:151], v[102:105], v[80:95]
	ds_read_b128 v[148:151], v173 offset:32896
	ds_read_b128 v[152:155], v173 offset:45184
	s_waitcnt lgkmcnt(0)
	v_mfma_f32_32x32x16_bf16 v[64:79], v[152:155], v[98:101], v[64:79]
	v_mfma_f32_32x32x16_bf16 v[80:95], v[148:151], v[98:101], v[80:95]
	ds_read_b128 v[148:151], v184 offset:33024
	ds_read_b128 v[152:155], v184 offset:45312
	ds_read_b128 v[218:221], v181
	s_waitcnt lgkmcnt(0)
; template <int D0> __device__ __forceinline__ void pv_one(f32x16& od, int vb, bf16x8 pa0, bf16x8 pa1, bf16x8 pa2, bf16x8 pa3) {
;     const s16x4 l0 = tr_read<v_rd_off(D0, 0, 0)>(vb), h0 = tr_read<v_rd_off(D0, 0, 1)>(vb), l1 = tr_read<v_rd_off(D0, 1, 0)>(vb), h1 = tr_read<v_rd_off(D0, 1, 1)>(vb);
;     const s16x4 l2 = tr_read<v_rd_off(D0, 2, 0)>(vb), h2 = tr_read<v_rd_off(D0, 2, 1)>(vb), l3 = tr_read<v_rd_off(D0, 3, 0)>(vb), h3 = tr_read<v_rd_off(D0, 3, 1)>(vb);
;     asm volatile("s_waitcnt lgkmcnt(0)" ::: "memory"); SBAR();
;     ...
;     od = __builtin_amdgcn_mfma_f32_32x32x16_bf16(pa0, PK(l0, h0), od, 0, 0, 0);
;     od = __builtin_amdgcn_mfma_f32_32x32x16_bf16(pa1, PK(l1, h1), od, 0, 0, 0);
;     od = __builtin_amdgcn_mfma_f32_32x32x16_bf16(pa2, PK(l2, h2), od, 0, 0, 0);
;     od = __builtin_amdgcn_mfma_f32_32x32x16_bf16(pa3, PK(l3, h3), od, 0, 0, 0);
;     ...
; }
; __device__ __forceinline__ void pv_d0(f32x16* o, int vb, bf16x8 pa0, bf16x8 pa1, bf16x8 pa2, bf16x8 pa3) {
;     pv_one<0>(o[0], vb, pa0, pa1, pa2, pa3); pv_one<1>(o[1], vb, pa0, pa1, pa2, pa3); pv_one<2>(o[2], vb, pa0, pa1, pa2, pa3); pv_one<3>(o[3], vb, pa0, pa1, pa2, pa3);
; }
; __device__ __forceinline__ void partialSM(f32x16& p0, f32x16& p1, float& m_reg, float& mn, float& alpha, const float C, const float thr) {
;     float pmax = p0[0];
; #pragma unroll
;     for (int r = 1; r < 16; ++r) pmax = fmaxf(pmax, p0[r]);
; #pragma unroll
;     for (int r = 0; r < 16; ++r) pmax = fmaxf(pmax, p1[r]);
;     { auto rr = __builtin_amdgcn_permlane32_swap(__float_as_uint(pmax), __float_as_uint(pmax), false, false);
;       pmax = fmaxf(__uint_as_float(rr[0]), __uint_as_float(rr[1])); }
;     if (__builtin_expect(__all(pmax - m_reg <= thr), 1)) { mn = m_reg; alpha = 1.f; }
;     else { mn = fmaxf(m_reg, pmax); alpha = __builtin_amdgcn_exp2f((m_reg - mn) * C); m_reg = mn; }
;     const float mnC = -mn * C;
; #pragma unroll
;     for (int r = 0; r < 16; ++r) p0[r] = fmaf(p0[r], C, mnC);
; #pragma unroll
;     for (int r = 0; r < 16; ++r) p1[r] = fmaf(p1[r], C, mnC);
; #pragma unroll
;     for (int r = 0; r < 16; ++r) p0[r] = __builtin_amdgcn_exp2f(p0[r]);
; }
; __device__ __forceinline__ void finishSM(f32x16& p0, f32x16& p1, float alpha, float& l_reg, bf16x8& pa0, bf16x8& pa1, bf16x8& pa2, bf16x8& pa3) {
; #pragma unroll
;     for (int r = 0; r < 16; ++r) p1[r] = __builtin_amdgcn_exp2f(p1[r]);
;     float ps = 0;
	v_mfma_f32_32x32x16_bf16 v[64:79], v[152:155], v[218:221], v[64:79]
	v_mfma_f32_32x32x16_bf16 v[80:95], v[148:151], v[218:221], v[80:95]
	ds_read_b128 v[148:151], v192 offset:33024
	ds_read_b128 v[152:155], v192 offset:45312
	ds_read_b128 v[218:221], v181 offset:8192
	s_waitcnt lgkmcnt(0)
	v_mfma_f32_32x32x16_bf16 v[64:79], v[152:155], v[218:221], v[64:79]
	v_mfma_f32_32x32x16_bf16 v[80:95], v[148:151], v[218:221], v[80:95]
	ds_read_b128 v[148:151], v190 offset:33024
	ds_read_b128 v[152:155], v190 offset:45312
	ds_read_b128 v[218:221], v181 offset:16384
	s_waitcnt lgkmcnt(0)
	v_mfma_f32_32x32x16_bf16 v[64:79], v[152:155], v[218:221], v[64:79]
	v_mfma_f32_32x32x16_bf16 v[80:95], v[148:151], v[218:221], v[80:95]
	ds_read_b128 v[148:151], v173 offset:33024
	ds_read_b128 v[152:155], v173 offset:45312
	ds_read_b128 v[218:221], v181 offset:24576
	s_waitcnt lgkmcnt(0)
	v_mfma_f32_32x32x16_bf16 v[64:79], v[152:155], v[218:221], v[64:79]
	v_add_f32_e32 v154, 0, v130
	v_add_f32_e32 v154, v211, v154
	v_add_f32_e32 v154, v131, v154
	v_add_f32_e32 v154, v212, v154
	v_add_f32_e32 v154, v132, v154
	v_add_f32_e32 v154, v213, v154
	v_add_f32_e32 v154, v133, v154
	v_add_f32_e32 v154, v224, v154
	v_add_f32_e32 v154, v137, v154
	v_add_f32_e32 v154, v228, v154
	v_add_f32_e32 v154, v136, v154
	v_add_f32_e32 v154, v229, v154
	v_add_f32_e32 v154, v135, v154
	v_add_f32_e32 v154, v230, v154
	v_add_f32_e32 v154, v134, v154
	v_mfma_f32_32x32x16_bf16 v[80:95], v[148:151], v[218:221], v[80:95]
	v_exp_f32_e32 v148, v156
	v_add_f32_e32 v154, v231, v154
	v_add_f32_e32 v154, v145, v154
	v_exp_f32_e32 v149, v157
	v_add_f32_e32 v154, v147, v154
	v_add_f32_e32 v154, v144, v154
	v_exp_f32_e32 v150, v191
	v_add_f32_e32 v154, v148, v154
	v_add_f32_e32 v154, v143, v154
	v_exp_f32_e32 v151, v205
	v_add_f32_e32 v154, v149, v154
	v_add_f32_e32 v154, v140, v154
	v_exp_f32_e32 v152, v207
	v_add_f32_e32 v154, v150, v154
	v_add_f32_e32 v154, v139, v154
	v_exp_f32_e32 v153, v210
	v_add_f32_e32 v154, v151, v154
	v_add_f32_e32 v154, v146, v154
	v_add_f32_e32 v154, v152, v154
	v_add_f32_e32 v154, v142, v154
	v_add_f32_e32 v154, v153, v154
	v_add_f32_e32 v154, v141, v154
	v_add_f32_e32 v226, v138, v154
	v_mov_b32_e32 v227, v226
	v_cvt_pk_bf16_f32 v130, v130, v211
	v_cvt_pk_bf16_f32 v131, v131, v212
	v_cvt_pk_bf16_f32 v132, v132, v213
	s_nop 1
	v_permlane32_swap_b32_e32 v226, v227
	v_cvt_pk_bf16_f32 v133, v133, v224
	v_permlane32_swap_b32_e32 v130, v132
	v_cvt_pk_bf16_f32 v154, v137, v228
	v_cvt_pk_bf16_f32 v155, v136, v229
	v_cvt_pk_bf16_f32 v156, v135, v230
	v_cvt_pk_bf16_f32 v157, v134, v231
	v_cvt_pk_bf16_f32 v218, v145, v147
	v_cvt_pk_bf16_f32 v219, v144, v148
	v_cvt_pk_bf16_f32 v220, v143, v149
	v_cvt_pk_bf16_f32 v221, v140, v150
	v_cvt_pk_bf16_f32 v228, v139, v151
	v_cvt_pk_bf16_f32 v229, v146, v152
	v_cvt_pk_bf16_f32 v230, v142, v153
	v_cvt_pk_bf16_f32 v231, v141, v138
	v_permlane32_swap_b32_e32 v131, v133
	v_permlane32_swap_b32_e32 v154, v156
	v_permlane32_swap_b32_e32 v155, v157
	v_permlane32_swap_b32_e32 v218, v220
	v_permlane32_swap_b32_e32 v219, v221
	v_permlane32_swap_b32_e32 v228, v230
	v_permlane32_swap_b32_e32 v229, v231
	s_add_i32 s38, s69, 1
	s_cmp_lt_u32 s38, s68
	s_cselect_b32 s14, 0, s68
	s_cselect_b32 s15, s25, s28
	s_lshl_b32 s14, s14, 6
	s_sub_i32 s14, s15, s14
	s_add_i32 s14, s37, s14
	s_add_i32 s14, s14, 64
	s_ashr_i32 s15, s14, 31
	v_lshl_add_u64 v[134:135], s[14:15], 0, v[174:175]
	v_lshl_add_u64 v[136:137], v[176:177], 0, s[14:15]
	v_lshlrev_b64 v[134:135], 12, v[134:135]
	v_lshlrev_b64 v[136:137], 12, v[136:137]
	v_lshl_add_u64 v[134:135], v[178:179], 0, v[134:135]
	v_lshl_add_u64 v[138:139], v[178:179], 0, v[136:137]
	v_mad_i64_i32 v[142:143], s[20:21], v164, s14, 0
	v_mad_i64_i32 v[146:147], s[20:21], v168, s14, 0
	v_mad_i64_i32 v[150:151], s[14:15], v172, s14, 0
	global_load_dwordx4 v[134:137], v[134:135], off offset:256
	s_nop 0
	global_load_dwordx4 v[138:141], v[138:139], off offset:256
	v_lshl_add_u64 v[142:143], v[142:143], 1, v[162:163]
	v_lshl_add_u64 v[146:147], v[146:147], 1, v[166:167]
	v_lshl_add_u64 v[150:151], v[150:151], 1, v[170:171]
	global_load_dwordx4 v[142:145], v[142:143], off
	s_nop 0
	global_load_dwordx4 v[146:149], v[146:147], off
	s_nop 0
	global_load_dwordx4 v[150:153], v[150:151], off
	ds_read_b64_tr_b16 v[232:233], v169 offset:0
	ds_read_b64_tr_b16 v[234:235], v169 offset:0x800
	ds_read_b64_tr_b16 v[236:237], v169 offset:0x1000
	ds_read_b64_tr_b16 v[238:239], v169 offset:0x1800
	ds_read_b64_tr_b16 v[240:241], v169 offset:0x2000
	ds_read_b64_tr_b16 v[242:243], v169 offset:0x2800
	ds_read_b64_tr_b16 v[244:245], v169 offset:0x3000
	ds_read_b64_tr_b16 v[246:247], v169 offset:0x3800
	s_waitcnt lgkmcnt(0)
	s_nop 0
	v_mfma_f32_32x32x16_bf16 v[48:63], v[130:133], v[232:235], v[48:63]
	ds_read_b64_tr_b16 v[232:233], v169 offset:0x200
	ds_read_b64_tr_b16 v[234:235], v169 offset:0xa00
	v_max_f32_e32 v248, v81, v81
	v_max_f32_e32 v249, v80, v80
	v_max_f32_e32 v248, v249, v248
	v_max3_f32 v248, v248, v82, v83
	v_max3_f32 v248, v248, v84, v85
	v_max3_f32 v248, v248, v86, v87
	v_mfma_f32_32x32x16_bf16 v[48:63], v[154:157], v[236:239], v[48:63]
	ds_read_b64_tr_b16 v[236:237], v169 offset:0x1200
	ds_read_b64_tr_b16 v[238:239], v169 offset:0x1a00
	v_max3_f32 v248, v248, v88, v89
	v_max3_f32 v248, v248, v90, v91
	v_max3_f32 v248, v248, v92, v93
	v_max3_f32 v248, v248, v94, v95
	v_max3_f32 v248, v248, v64, v65
	v_max3_f32 v248, v248, v66, v67
	v_mfma_f32_32x32x16_bf16 v[48:63], v[218:221], v[240:243], v[48:63]
	ds_read_b64_tr_b16 v[240:241], v169 offset:0x2200
	ds_read_b64_tr_b16 v[242:243], v169 offset:0x2a00
	v_max3_f32 v248, v248, v68, v69
	v_max3_f32 v248, v248, v70, v71
	v_max3_f32 v248, v248, v72, v73
	v_max3_f32 v248, v248, v74, v75
	v_max3_f32 v248, v248, v76, v77
	v_max3_f32 v248, v248, v78, v79
	v_mfma_f32_32x32x16_bf16 v[48:63], v[228:231], v[244:247], v[48:63]
	ds_read_b64_tr_b16 v[244:245], v169 offset:0x3200
	ds_read_b64_tr_b16 v[246:247], v169 offset:0x3a00
	v_mov_b32_e32 v249, v248
	s_nop 1
	v_permlane32_swap_b32_e32 v248, v249
	v_max_f32_e32 v249, v249, v249
	v_max_f32_e32 v248, v248, v248
	v_max_f32_e32 v248, v248, v249
	s_waitcnt lgkmcnt(0)
; #define SBAR() __builtin_amdgcn_sched_barrier(0)
; #define SLOAD(i, j) do { const long rb_ = KROW(j); sr_[i].vs0 = *(const bf16x8*)(a.V + (rb_ + sr) * LDV + sc); sr_[i].vs1 = *(const bf16x8*)(a.V + (rb_ + 32 + sr) * LDV + sc); \
;     _Pragma("unroll") for (int c_ = 0; c_ < KCH; ++c_) sr_[i].ks[c_] = *(const bf16x8*)(kptr[c_] + rb_ * kld[c_]); } while (0)
; #define SWRITE(b, i) do { *(bf16x8*)(V_lds + (b) * SHM_V + vst0) = sr_[i].vs0; *(bf16x8*)(V_lds + (b) * SHM_V + vst1) = sr_[i].vs1; \
;     _Pragma("unroll") for (int c_ = 0; c_ < KCH; ++c_) *(bf16x8*)(K_lds + (b) * SHM_K + kwo[c_]) = sr_[i].ks[c_]; } while (0)
; __device__ __forceinline__ void partialSM(f32x16& p0, f32x16& p1, float& m_reg, float& mn, float& alpha, const float C, const float thr) {
;     float pmax = p0[0];
; #pragma unroll
;     for (int r = 1; r < 16; ++r) pmax = fmaxf(pmax, p0[r]);
; #pragma unroll
;     for (int r = 0; r < 16; ++r) pmax = fmaxf(pmax, p1[r]);
;     { auto rr = __builtin_amdgcn_permlane32_swap(__float_as_uint(pmax), __float_as_uint(pmax), false, false);
;       pmax = fmaxf(__uint_as_float(rr[0]), __uint_as_float(rr[1])); }
;     if (__builtin_expect(__all(pmax - m_reg <= thr), 1)) { mn = m_reg; alpha = 1.f; }
;     else { mn = fmaxf(m_reg, pmax); alpha = __builtin_amdgcn_exp2f((m_reg - mn) * C); m_reg = mn; }
;     const float mnC = -mn * C;
; #pragma unroll
;     for (int r = 0; r < 16; ++r) p0[r] = fmaf(p0[r], C, mnC);
; #pragma unroll
;     for (int r = 0; r < 16; ++r) p1[r] = fmaf(p1[r], C, mnC);
; #pragma unroll
;     for (int r = 0; r < 16; ++r) p0[r] = __builtin_amdgcn_exp2f(p0[r]);
; }
; __device__ __forceinline__ void finishSM(f32x16& p0, f32x16& p1, float alpha, float& l_reg, bf16x8& pa0, bf16x8& pa1, bf16x8& pa2, bf16x8& pa3) {
; #pragma unroll
;     for (int r = 0; r < 16; ++r) p1[r] = __builtin_amdgcn_exp2f(p1[r]);
; template <int DQK, int DK1, int LDQ, int LDK, int LDKR, int LDV, int NQL, int SDEPTH>
; __device__ __forceinline__ void attn_core(const AttnArgs& a, char* lds, f32x16 (&o)[4]) {
;     ...
;         finishSM(pB0, pB1, alB, l_reg, pa0, pa1, pa2, pa3); SBAR();
;         if (SDEPTH == 1 || j + 3 < NT) SLOAD(SE, j + 1 + SDEPTH); SBAR();
;         pv_d0(o, vb0 + SHM_V, pa0, pa1, pa2, pa3); partialSM(pA0, pA1, m_reg, mnA, alA, a.C, a.thr);
;         __syncthreads(); SWRITE(1, SO);
;         RESC(alA); __syncthreads();
	v_mfma_f32_32x32x16_bf16 v[32:47], v[130:133], v[232:235], v[32:47]
	ds_read_b64_tr_b16 v[232:233], v169 offset:0x400
	ds_read_b64_tr_b16 v[234:235], v169 offset:0xc00
	v_sub_f32_e32 v249, v248, v204
	v_cmp_ge_f32_e32 vcc, s72, v249
	v_max_f32_e32 v249, v204, v204
	v_max_f32_e32 v248, v249, v248
	v_sub_f32_e32 v249, v204, v248
	v_mul_f32_e32 v249, 0x3dd53b94, v249
	v_mfma_f32_32x32x16_bf16 v[32:47], v[154:157], v[236:239], v[32:47]
	ds_read_b64_tr_b16 v[236:237], v169 offset:0x1400
	ds_read_b64_tr_b16 v[238:239], v169 offset:0x1c00
	v_exp_f32_e32 v249, v249
	s_cmp_eq_u64 vcc, exec
	s_cselect_b64 s[14:15], -1, 0
	v_cndmask_b32_e64 v224, v249, 1.0, s[14:15]
	v_cmp_gt_f32_e32 vcc, 1.0, v224
	v_mfma_f32_32x32x16_bf16 v[32:47], v[218:221], v[240:243], v[32:47]
	ds_read_b64_tr_b16 v[240:241], v169 offset:0x2400
	ds_read_b64_tr_b16 v[242:243], v169 offset:0x2c00
	v_cndmask_b32_e64 v251, v248, v204, s[14:15]
	v_mul_f32_e32 v249, 0xbdd53b94, v251
	v_fmamk_f32 v80, v80, 0x3dd53b94, v249
	v_fmamk_f32 v81, v81, 0x3dd53b94, v249
	v_mfma_f32_32x32x16_bf16 v[32:47], v[228:231], v[244:247], v[32:47]
	ds_read_b64_tr_b16 v[244:245], v169 offset:0x3400
	ds_read_b64_tr_b16 v[246:247], v169 offset:0x3c00
	v_fmamk_f32 v82, v82, 0x3dd53b94, v249
	v_fmamk_f32 v83, v83, 0x3dd53b94, v249
	v_fmamk_f32 v84, v84, 0x3dd53b94, v249
	v_fmamk_f32 v85, v85, 0x3dd53b94, v249
	s_waitcnt lgkmcnt(0)
	v_mfma_f32_32x32x16_bf16 v[16:31], v[130:133], v[232:235], v[16:31]
	ds_read_b64_tr_b16 v[232:233], v169 offset:0x600
	ds_read_b64_tr_b16 v[234:235], v169 offset:0xe00
	v_fmamk_f32 v86, v86, 0x3dd53b94, v249
	v_fmamk_f32 v87, v87, 0x3dd53b94, v249
	v_fmamk_f32 v88, v88, 0x3dd53b94, v249
	v_fmamk_f32 v89, v89, 0x3dd53b94, v249
	v_mfma_f32_32x32x16_bf16 v[16:31], v[154:157], v[236:239], v[16:31]
	ds_read_b64_tr_b16 v[236:237], v169 offset:0x1600
	ds_read_b64_tr_b16 v[238:239], v169 offset:0x1e00
	v_fmamk_f32 v90, v90, 0x3dd53b94, v249
	v_fmamk_f32 v91, v91, 0x3dd53b94, v249
	v_fmamk_f32 v92, v92, 0x3dd53b94, v249
	v_fmamk_f32 v93, v93, 0x3dd53b94, v249
	v_mfma_f32_32x32x16_bf16 v[16:31], v[218:221], v[240:243], v[16:31]
	ds_read_b64_tr_b16 v[240:241], v169 offset:0x2600
	ds_read_b64_tr_b16 v[242:243], v169 offset:0x2e00
	v_fmamk_f32 v94, v94, 0x3dd53b94, v249
	v_mfma_f32_32x32x16_bf16 v[16:31], v[228:231], v[244:247], v[16:31]
	ds_read_b64_tr_b16 v[244:245], v169 offset:0x3600
	ds_read_b64_tr_b16 v[246:247], v169 offset:0x3e00
	s_waitcnt lgkmcnt(0)
	v_mfma_f32_32x32x16_bf16 v[0:15], v[130:133], v[232:235], v[0:15]
	v_mfma_f32_32x32x16_bf16 v[0:15], v[154:157], v[236:239], v[0:15]
	v_mfma_f32_32x32x16_bf16 v[0:15], v[218:221], v[240:243], v[0:15]
	v_mfma_f32_32x32x16_bf16 v[0:15], v[228:231], v[244:247], v[0:15]
	s_barrier
	s_waitcnt vmcnt(4)
	ds_write_b128 v186, v[134:137] offset:16384
	s_waitcnt vmcnt(3)
	ds_write_b128 v188, v[138:141] offset:16384
	s_waitcnt vmcnt(2)
	ds_write_b128 v194, v[142:145] offset:57344
	s_waitcnt vmcnt(1)
	ds_write_b128 v196, v[146:149] offset:57344
	s_waitcnt vmcnt(0)
	ds_write_b128 v198, v[150:153] offset:57344
	s_cbranch_vccz .LBB0_227
	s_and_saveexec_b64 s[20:21], s[12:13]
	ds_write_b32 v165, v224 offset:128
	s_or_b64 exec, exec, s[20:21]
	s_waitcnt lgkmcnt(0)
	v_add_u32_e32 v131, v161, v96
	ds_read_b128 v[132:135], v131 offset:224
	ds_read_b128 v[136:139], v131 offset:192
	ds_read_b128 v[140:143], v131 offset:160
	ds_read_b128 v[144:147], v131 offset:128
	s_waitcnt lgkmcnt(3)
	v_pk_mul_f32 v[60:61], v[60:61], v[132:133]
	s_waitcnt lgkmcnt(2)
	v_pk_mul_f32 v[56:57], v[56:57], v[136:137]
	s_waitcnt lgkmcnt(1)
	v_pk_mul_f32 v[52:53], v[52:53], v[140:141]
	v_pk_mul_f32 v[62:63], v[62:63], v[134:135]
	v_pk_mul_f32 v[58:59], v[58:59], v[138:139]
	v_pk_mul_f32 v[54:55], v[54:55], v[142:143]
	s_waitcnt lgkmcnt(0)
	v_pk_mul_f32 v[50:51], v[50:51], v[146:147]
	v_pk_mul_f32 v[48:49], v[48:49], v[144:145]
	v_pk_mul_f32 v[44:45], v[44:45], v[132:133]
	v_pk_mul_f32 v[40:41], v[40:41], v[136:137]
	v_pk_mul_f32 v[36:37], v[36:37], v[140:141]
	v_pk_mul_f32 v[46:47], v[46:47], v[134:135]
	v_pk_mul_f32 v[42:43], v[42:43], v[138:139]
	v_pk_mul_f32 v[38:39], v[38:39], v[142:143]
	v_pk_mul_f32 v[34:35], v[34:35], v[146:147]
	v_pk_mul_f32 v[32:33], v[32:33], v[144:145]
	v_pk_mul_f32 v[28:29], v[28:29], v[132:133]
	v_pk_mul_f32 v[24:25], v[24:25], v[136:137]
	v_pk_mul_f32 v[20:21], v[20:21], v[140:141]
	v_pk_mul_f32 v[30:31], v[30:31], v[134:135]
	v_pk_mul_f32 v[26:27], v[26:27], v[138:139]
	v_pk_mul_f32 v[22:23], v[22:23], v[142:143]
	v_pk_mul_f32 v[18:19], v[18:19], v[146:147]
	v_pk_mul_f32 v[16:17], v[16:17], v[144:145]
	v_pk_mul_f32 v[12:13], v[12:13], v[132:133]
	v_pk_mul_f32 v[8:9], v[8:9], v[136:137]
	v_pk_mul_f32 v[4:5], v[4:5], v[140:141]
	v_pk_mul_f32 v[14:15], v[14:15], v[134:135]
	v_pk_mul_f32 v[10:11], v[10:11], v[138:139]
	v_pk_mul_f32 v[6:7], v[6:7], v[142:143]
	v_pk_mul_f32 v[2:3], v[2:3], v[146:147]
	v_pk_mul_f32 v[0:1], v[0:1], v[144:145]
.LBB0_227:
	v_cndmask_b32_e64 v204, v248, v204, s[14:15]
	v_mul_f32_e32 v136, 0xbdd53b94, v204
	v_mov_b32_e32 v137, v136
	v_fmac_f32_e32 v137, 0x3dd53b94, v95
	v_exp_f32_e32 v219, v80
	v_exp_f32_e32 v221, v81
	v_exp_f32_e32 v157, v82
	v_exp_f32_e32 v220, v83
	v_exp_f32_e32 v156, v84
	v_exp_f32_e32 v218, v85
	v_exp_f32_e32 v154, v86
	v_exp_f32_e32 v155, v87
	v_exp_f32_e32 v151, v88
	v_exp_f32_e32 v153, v89
	v_exp_f32_e32 v150, v90
	v_exp_f32_e32 v152, v91
	v_exp_f32_e32 v147, v92
	v_exp_f32_e32 v149, v93
	v_exp_f32_e32 v146, v94
	v_exp_f32_e32 v148, v137
	v_pk_fma_f32 v[142:143], v[64:65], s[60:61], v[136:137] op_sel_hi:[1,0,0]
	v_add_f32_e32 v64, v222, v223
	v_fmac_f32_e32 v64, v217, v182
	v_add_f32_e32 v182, v226, v227
	s_addk_i32 s37, 0x80
	s_add_i32 s69, s38, 1
	v_pk_fma_f32 v[140:141], v[66:67], s[60:61], v[136:137] op_sel_hi:[1,0,0]
	v_pk_fma_f32 v[134:135], v[68:69], s[60:61], v[136:137] op_sel_hi:[1,0,0]
	v_pk_fma_f32 v[132:133], v[70:71], s[60:61], v[136:137] op_sel_hi:[1,0,0]
	v_pk_fma_f32 v[130:131], v[72:73], s[60:61], v[136:137] op_sel_hi:[1,0,0]
	v_pk_fma_f32 v[144:145], v[74:75], s[60:61], v[136:137] op_sel_hi:[1,0,0]
	v_pk_fma_f32 v[138:139], v[76:77], s[60:61], v[136:137] op_sel_hi:[1,0,0]
	v_pk_fma_f32 v[136:137], v[78:79], s[60:61], v[136:137] op_sel_hi:[1,0,0]
	v_fmac_f32_e32 v182, v64, v225
	s_cmp_ge_u32 s69, s29
	s_waitcnt lgkmcnt(0)
	s_barrier
	s_cbranch_scc1 .LBB0_229
	v_mov_b32_e32 v217, v224
	s_branch .LBB0_219
